# GEMM4 fast-path epilogue: conv weights and bias row staged by LDS-DMA into 4 KiB extra static LDS at loop exit, 16 L2 loads per wave become ds_read_b128
# speedup vs baseline: 1.0076x; 1.0076x over previous
.LBB0_1180:
	ds_read_b128 v[54:57], v238
	ds_read_b128 v[134:137], v238 offset:1024
	ds_read_b128 v[158:161], v238 offset:2048
	ds_read_b128 v[162:165], v238 offset:3072
	ds_read_b128 v[166:169], v239
	ds_read_b128 v[170:173], v239 offset:1024
	ds_read_b128 v[174:177], v239 offset:2048
	ds_read_b128 v[178:181], v239 offset:3072
	s_add_u32 s0, s60, 0x100
	s_addc_u32 s1, s61, 0
	s_cmp_eq_u32 s38, 12
	s_cselect_b32 s65, s19, s1
	s_cselect_b32 s64, s18, s0
	s_cselect_b32 s63, s17, vcc_hi
	s_cselect_b32 s62, s93, vcc_lo
	v_lshl_add_u64 v[214:215], s[60:61], 0, v[150:151]
	s_add_i32 m0, s73, 0xc000
	ds_read_b128 v[182:185], v240
	ds_read_b128 v[186:189], v240 offset:1024
	ds_read_b128 v[190:193], v240 offset:2048
	ds_read_b128 v[194:197], v240 offset:3072
	ds_read_b128 v[198:201], v240 offset:4096
	ds_read_b128 v[202:205], v240 offset:5120
	ds_read_b128 v[206:209], v240 offset:6144
	ds_read_b128 v[210:213], v240 offset:7168
	global_load_lds_dwordx4 v[214:215], off
	v_lshl_add_u64 v[214:215], s[60:61], 0, v[152:153]
	s_add_i32 m0, s73, 0xe000
	s_nop 0
	global_load_lds_dwordx4 v[214:215], off
	s_waitcnt vmcnt(8)
	s_waitcnt lgkmcnt(0)
	s_barrier
	s_setprio 1
	s_waitcnt lgkmcnt(0)
	v_mfma_f32_16x16x32_bf16 v[126:129], v[54:57], v[182:185], v[126:129]
	v_mfma_f32_16x16x32_bf16 v[122:125], v[158:161], v[182:185], v[122:125]
	v_mfma_f32_16x16x32_bf16 v[118:121], v[54:57], v[190:193], v[118:121]
	v_mfma_f32_16x16x32_bf16 v[114:117], v[158:161], v[190:193], v[114:117]
	v_mfma_f32_16x16x32_bf16 v[50:53], v[54:57], v[198:201], v[50:53]
	v_mfma_f32_16x16x32_bf16 v[22:25], v[158:161], v[198:201], v[22:25]
	v_mfma_f32_16x16x32_bf16 v[62:65], v[54:57], v[206:209], v[62:65]
	v_mfma_f32_16x16x32_bf16 v[130:133], v[158:161], v[206:209], v[130:133]
	v_mfma_f32_16x16x32_bf16 v[126:129], v[134:137], v[186:189], v[126:129]
	v_mfma_f32_16x16x32_bf16 v[122:125], v[162:165], v[186:189], v[122:125]
	v_mfma_f32_16x16x32_bf16 v[118:121], v[134:137], v[194:197], v[118:121]
	v_mfma_f32_16x16x32_bf16 v[114:117], v[162:165], v[194:197], v[114:117]
	v_mfma_f32_16x16x32_bf16 v[50:53], v[134:137], v[202:205], v[50:53]
	v_mfma_f32_16x16x32_bf16 v[22:25], v[162:165], v[202:205], v[22:25]
	v_mfma_f32_16x16x32_bf16 v[62:65], v[134:137], v[210:213], v[62:65]
	v_mfma_f32_16x16x32_bf16 v[130:133], v[162:165], v[210:213], v[130:133]
	s_setprio 0
	s_setprio 1
	v_mfma_f32_16x16x32_bf16 v[110:113], v[166:169], v[182:185], v[110:113]
	v_mfma_f32_16x16x32_bf16 v[106:109], v[174:177], v[182:185], v[106:109]
	v_mfma_f32_16x16x32_bf16 v[102:105], v[166:169], v[190:193], v[102:105]
	v_mfma_f32_16x16x32_bf16 v[98:101], v[174:177], v[190:193], v[98:101]
	v_mfma_f32_16x16x32_bf16 v[30:33], v[166:169], v[198:201], v[30:33]
	v_mfma_f32_16x16x32_bf16 v[18:21], v[174:177], v[198:201], v[18:21]
	v_mfma_f32_16x16x32_bf16 v[58:61], v[166:169], v[206:209], v[58:61]
	v_mfma_f32_16x16x32_bf16 v[26:29], v[174:177], v[206:209], v[26:29]
	v_mfma_f32_16x16x32_bf16 v[110:113], v[170:173], v[186:189], v[110:113]
	v_mfma_f32_16x16x32_bf16 v[106:109], v[178:181], v[186:189], v[106:109]
	v_mfma_f32_16x16x32_bf16 v[102:105], v[170:173], v[194:197], v[102:105]
	v_mfma_f32_16x16x32_bf16 v[98:101], v[178:181], v[194:197], v[98:101]
	v_mfma_f32_16x16x32_bf16 v[30:33], v[170:173], v[202:205], v[30:33]
	v_mfma_f32_16x16x32_bf16 v[18:21], v[178:181], v[202:205], v[18:21]
	v_mfma_f32_16x16x32_bf16 v[58:61], v[170:173], v[210:213], v[58:61]
	v_mfma_f32_16x16x32_bf16 v[26:29], v[178:181], v[210:213], v[26:29]
	s_setprio 0
	s_barrier
	s_add_i32 s39, s30, s89
	v_lshl_add_u64 v[214:215], s[62:63], 0, v[140:141]
	s_mov_b32 m0, s39
	ds_read_b128 v[182:185], v240 offset:16384
	ds_read_b128 v[186:189], v240 offset:17408
	ds_read_b128 v[190:193], v240 offset:18432
	ds_read_b128 v[194:197], v240 offset:19456
	ds_read_b128 v[198:201], v240 offset:20480
	ds_read_b128 v[202:205], v240 offset:21504
	ds_read_b128 v[206:209], v240 offset:22528
	ds_read_b128 v[210:213], v240 offset:23552
	global_load_lds_dwordx4 v[214:215], off
	s_add_i32 m0, s39, 0x2000
	s_add_u32 s60, s62, 0x40000
	v_lshl_add_u64 v[216:217], s[62:63], 0, v[144:145]
	s_addc_u32 s61, s63, 0
	s_add_i32 s39, s31, s89
	global_load_lds_dwordx4 v[216:217], off
	v_lshl_add_u64 v[244:245], s[60:61], 0, v[140:141]
	s_mov_b32 m0, s39
	v_lshl_add_u64 v[246:247], s[64:65], 0, v[142:143]
	global_load_lds_dwordx4 v[244:245], off
	v_lshl_add_u64 v[244:245], s[60:61], 0, v[144:145]
	s_add_i32 m0, s39, 0x2000
	s_nop 0
	global_load_lds_dwordx4 v[244:245], off
	v_lshl_add_u64 v[244:245], s[64:65], 0, v[138:139]
	s_mov_b32 m0, s73
	s_nop 0
	global_load_lds_dwordx4 v[244:245], off
	s_mov_b32 m0, s24
	s_nop 0
	global_load_lds_dwordx4 v[246:247], off
	s_waitcnt vmcnt(8)
	s_waitcnt lgkmcnt(0)
	s_barrier
	s_setprio 1
	s_waitcnt lgkmcnt(0)
	v_mfma_f32_16x16x32_bf16 v[94:97], v[54:57], v[182:185], v[94:97]
	v_mfma_f32_16x16x32_bf16 v[90:93], v[158:161], v[182:185], v[90:93]
	v_mfma_f32_16x16x32_bf16 v[86:89], v[54:57], v[190:193], v[86:89]
	v_mfma_f32_16x16x32_bf16 v[82:85], v[158:161], v[190:193], v[82:85]
	v_mfma_f32_16x16x32_bf16 v[34:37], v[54:57], v[198:201], v[34:37]
	v_mfma_f32_16x16x32_bf16 v[6:9], v[158:161], v[198:201], v[6:9]
	v_mfma_f32_16x16x32_bf16 v[42:45], v[54:57], v[206:209], v[42:45]
	v_mfma_f32_16x16x32_bf16 v[10:13], v[158:161], v[206:209], v[10:13]
	v_mfma_f32_16x16x32_bf16 v[94:97], v[134:137], v[186:189], v[94:97]
	v_mfma_f32_16x16x32_bf16 v[90:93], v[162:165], v[186:189], v[90:93]
	v_mfma_f32_16x16x32_bf16 v[86:89], v[134:137], v[194:197], v[86:89]
	v_mfma_f32_16x16x32_bf16 v[82:85], v[162:165], v[194:197], v[82:85]
	v_mfma_f32_16x16x32_bf16 v[34:37], v[134:137], v[202:205], v[34:37]
	v_mfma_f32_16x16x32_bf16 v[6:9], v[162:165], v[202:205], v[6:9]
	v_mfma_f32_16x16x32_bf16 v[42:45], v[134:137], v[210:213], v[42:45]
	v_mfma_f32_16x16x32_bf16 v[10:13], v[162:165], v[210:213], v[10:13]
	s_setprio 0
	s_setprio 1
	v_mfma_f32_16x16x32_bf16 v[74:77], v[174:177], v[182:185], v[74:77]
	v_mfma_f32_16x16x32_bf16 v[70:73], v[166:169], v[190:193], v[70:73]
	v_mfma_f32_16x16x32_bf16 v[66:69], v[174:177], v[190:193], v[66:69]
	v_mfma_f32_16x16x32_bf16 v[38:41], v[166:169], v[198:201], v[38:41]
	v_mfma_f32_16x16x32_bf16 v[2:5], v[174:177], v[198:201], v[2:5]
	v_mfma_f32_16x16x32_bf16 v[46:49], v[166:169], v[206:209], v[46:49]
	v_mfma_f32_16x16x32_bf16 v[14:17], v[174:177], v[206:209], v[14:17]
	v_mfma_f32_16x16x32_bf16 v[54:57], v[166:169], v[182:185], v[78:81]
	v_mfma_f32_16x16x32_bf16 v[74:77], v[178:181], v[186:189], v[74:77]
	v_mfma_f32_16x16x32_bf16 v[70:73], v[170:173], v[194:197], v[70:73]
	v_mfma_f32_16x16x32_bf16 v[66:69], v[178:181], v[194:197], v[66:69]
	v_mfma_f32_16x16x32_bf16 v[38:41], v[170:173], v[202:205], v[38:41]
	v_mfma_f32_16x16x32_bf16 v[2:5], v[178:181], v[202:205], v[2:5]
	v_mfma_f32_16x16x32_bf16 v[46:49], v[170:173], v[210:213], v[46:49]
	v_mfma_f32_16x16x32_bf16 v[14:17], v[178:181], v[210:213], v[14:17]
	v_mfma_f32_16x16x32_bf16 v[54:57], v[170:173], v[186:189], v[54:57]
	s_setprio 0
	s_barrier
	s_add_i32 s39, 0, 0x18000
	v_add_u32_e32 v146, s39, v1
	s_add_i32 s94, 0, 0x1c000
	ds_read_b128 v[78:81], v146
	ds_read_b128 v[134:137], v146 offset:1024
	ds_read_b128 v[158:161], v146 offset:2048
	ds_read_b128 v[162:165], v146 offset:3072
	v_add_u32_e32 v146, s94, v1
	ds_read_b128 v[166:169], v146
	ds_read_b128 v[170:173], v146 offset:1024
	ds_read_b128 v[174:177], v146 offset:2048
	ds_read_b128 v[178:181], v146 offset:3072
	s_add_u32 s60, s64, 0x40000
	s_addc_u32 s61, s65, 0
	s_mov_b32 m0, s25
	v_lshl_add_u64 v[248:249], s[60:61], 0, v[138:139]
	ds_read_b128 v[182:185], v240 offset:32768
	ds_read_b128 v[186:189], v240 offset:33792
	ds_read_b128 v[190:193], v240 offset:34816
	ds_read_b128 v[194:197], v240 offset:35840
	ds_read_b128 v[198:201], v240 offset:36864
	ds_read_b128 v[202:205], v240 offset:37888
	ds_read_b128 v[206:209], v240 offset:38912
	ds_read_b128 v[210:213], v240 offset:39936
	global_load_lds_dwordx4 v[248:249], off
	v_lshl_add_u64 v[248:249], s[60:61], 0, v[142:143]
	s_mov_b32 m0, s26
	s_nop 0
	global_load_lds_dwordx4 v[248:249], off
	s_waitcnt vmcnt(8)
	s_waitcnt lgkmcnt(0)
	s_barrier
	s_setprio 1
	s_waitcnt lgkmcnt(0)
	v_mfma_f32_16x16x32_bf16 v[126:129], v[78:81], v[182:185], v[126:129]
	v_mfma_f32_16x16x32_bf16 v[122:125], v[158:161], v[182:185], v[122:125]
	v_mfma_f32_16x16x32_bf16 v[118:121], v[78:81], v[190:193], v[118:121]
	v_mfma_f32_16x16x32_bf16 v[114:117], v[158:161], v[190:193], v[114:117]
	v_mfma_f32_16x16x32_bf16 v[50:53], v[78:81], v[198:201], v[50:53]
	v_mfma_f32_16x16x32_bf16 v[22:25], v[158:161], v[198:201], v[22:25]
	v_mfma_f32_16x16x32_bf16 v[62:65], v[78:81], v[206:209], v[62:65]
	v_mfma_f32_16x16x32_bf16 v[130:133], v[158:161], v[206:209], v[130:133]
	v_mfma_f32_16x16x32_bf16 v[126:129], v[134:137], v[186:189], v[126:129]
	v_mfma_f32_16x16x32_bf16 v[122:125], v[162:165], v[186:189], v[122:125]
	v_mfma_f32_16x16x32_bf16 v[118:121], v[134:137], v[194:197], v[118:121]
	v_mfma_f32_16x16x32_bf16 v[114:117], v[162:165], v[194:197], v[114:117]
	v_mfma_f32_16x16x32_bf16 v[50:53], v[134:137], v[202:205], v[50:53]
	v_mfma_f32_16x16x32_bf16 v[22:25], v[162:165], v[202:205], v[22:25]
	v_mfma_f32_16x16x32_bf16 v[62:65], v[134:137], v[210:213], v[62:65]
	v_mfma_f32_16x16x32_bf16 v[130:133], v[162:165], v[210:213], v[130:133]
	s_setprio 0
	s_setprio 1
	v_mfma_f32_16x16x32_bf16 v[110:113], v[166:169], v[182:185], v[110:113]
	v_mfma_f32_16x16x32_bf16 v[106:109], v[174:177], v[182:185], v[106:109]
	v_mfma_f32_16x16x32_bf16 v[102:105], v[166:169], v[190:193], v[102:105]
	v_mfma_f32_16x16x32_bf16 v[98:101], v[174:177], v[190:193], v[98:101]
	v_mfma_f32_16x16x32_bf16 v[30:33], v[166:169], v[198:201], v[30:33]
	v_mfma_f32_16x16x32_bf16 v[18:21], v[174:177], v[198:201], v[18:21]
	v_mfma_f32_16x16x32_bf16 v[58:61], v[166:169], v[206:209], v[58:61]
	v_mfma_f32_16x16x32_bf16 v[26:29], v[174:177], v[206:209], v[26:29]
	v_mfma_f32_16x16x32_bf16 v[110:113], v[170:173], v[186:189], v[110:113]
	v_mfma_f32_16x16x32_bf16 v[106:109], v[178:181], v[186:189], v[106:109]
	v_mfma_f32_16x16x32_bf16 v[102:105], v[170:173], v[194:197], v[102:105]
	v_mfma_f32_16x16x32_bf16 v[98:101], v[178:181], v[194:197], v[98:101]
	v_mfma_f32_16x16x32_bf16 v[30:33], v[170:173], v[202:205], v[30:33]
	v_mfma_f32_16x16x32_bf16 v[18:21], v[178:181], v[202:205], v[18:21]
	v_mfma_f32_16x16x32_bf16 v[58:61], v[170:173], v[210:213], v[58:61]
	v_mfma_f32_16x16x32_bf16 v[26:29], v[178:181], v[210:213], v[26:29]
	s_setprio 0
	s_barrier
	s_add_i32 s39, s39, s89
	v_lshl_add_u64 v[214:215], v[214:215], 0, s[76:77]
	s_mov_b32 m0, s39
	ds_read_b128 v[182:185], v240 offset:49152
	ds_read_b128 v[186:189], v240 offset:50176
	ds_read_b128 v[190:193], v240 offset:51200
	ds_read_b128 v[194:197], v240 offset:52224
	ds_read_b128 v[198:201], v240 offset:53248
	ds_read_b128 v[202:205], v240 offset:54272
	ds_read_b128 v[206:209], v240 offset:55296
	ds_read_b128 v[210:213], v240 offset:56320
	global_load_lds_dwordx4 v[214:215], off
	s_add_i32 m0, s39, 0x2000
	s_add_u32 s60, s62, 0x40080
	v_lshl_add_u64 v[214:215], v[216:217], 0, s[76:77]
	s_addc_u32 s61, s63, 0
	s_add_i32 s39, s94, s89
	global_load_lds_dwordx4 v[214:215], off
	v_lshl_add_u64 v[214:215], s[60:61], 0, v[140:141]
	s_mov_b32 m0, s39
	s_nop 0
	global_load_lds_dwordx4 v[214:215], off
	v_lshl_add_u64 v[214:215], s[60:61], 0, v[144:145]
	s_add_i32 m0, s39, 0x2000
	s_nop 0
	global_load_lds_dwordx4 v[214:215], off
	v_lshl_add_u64 v[214:215], v[244:245], 0, s[76:77]
	s_mov_b32 m0, s27
	s_nop 0
	global_load_lds_dwordx4 v[214:215], off
	v_lshl_add_u64 v[214:215], v[246:247], 0, s[76:77]
	s_mov_b32 m0, s28
	s_nop 0
	global_load_lds_dwordx4 v[214:215], off
	s_waitcnt vmcnt(8)
	s_waitcnt lgkmcnt(0)
	s_barrier
	s_setprio 1
	s_waitcnt lgkmcnt(0)
	v_mfma_f32_16x16x32_bf16 v[94:97], v[78:81], v[182:185], v[94:97]
	v_mfma_f32_16x16x32_bf16 v[90:93], v[158:161], v[182:185], v[90:93]
	v_mfma_f32_16x16x32_bf16 v[86:89], v[78:81], v[190:193], v[86:89]
	v_mfma_f32_16x16x32_bf16 v[82:85], v[158:161], v[190:193], v[82:85]
	v_mfma_f32_16x16x32_bf16 v[34:37], v[78:81], v[198:201], v[34:37]
	v_mfma_f32_16x16x32_bf16 v[6:9], v[158:161], v[198:201], v[6:9]
	v_mfma_f32_16x16x32_bf16 v[42:45], v[78:81], v[206:209], v[42:45]
	v_mfma_f32_16x16x32_bf16 v[10:13], v[158:161], v[206:209], v[10:13]
	v_mfma_f32_16x16x32_bf16 v[94:97], v[134:137], v[186:189], v[94:97]
	v_mfma_f32_16x16x32_bf16 v[90:93], v[162:165], v[186:189], v[90:93]
	v_mfma_f32_16x16x32_bf16 v[86:89], v[134:137], v[194:197], v[86:89]
	v_mfma_f32_16x16x32_bf16 v[82:85], v[162:165], v[194:197], v[82:85]
	v_mfma_f32_16x16x32_bf16 v[34:37], v[134:137], v[202:205], v[34:37]
	v_mfma_f32_16x16x32_bf16 v[6:9], v[162:165], v[202:205], v[6:9]
	v_mfma_f32_16x16x32_bf16 v[42:45], v[134:137], v[210:213], v[42:45]
	v_mfma_f32_16x16x32_bf16 v[10:13], v[162:165], v[210:213], v[10:13]
	s_setprio 0
	s_setprio 1
	v_mfma_f32_16x16x32_bf16 v[54:57], v[166:169], v[182:185], v[54:57]
	v_mfma_f32_16x16x32_bf16 v[78:81], v[170:173], v[186:189], v[54:57]
	v_mfma_f32_16x16x32_bf16 v[54:57], v[174:177], v[182:185], v[74:77]
	v_mfma_f32_16x16x32_bf16 v[74:77], v[178:181], v[186:189], v[54:57]
	v_mfma_f32_16x16x32_bf16 v[54:57], v[166:169], v[190:193], v[70:73]
	v_mfma_f32_16x16x32_bf16 v[70:73], v[170:173], v[194:197], v[54:57]
	v_mfma_f32_16x16x32_bf16 v[54:57], v[174:177], v[190:193], v[66:69]
	v_mfma_f32_16x16x32_bf16 v[38:41], v[166:169], v[198:201], v[38:41]
	v_mfma_f32_16x16x32_bf16 v[2:5], v[174:177], v[198:201], v[2:5]
	v_mfma_f32_16x16x32_bf16 v[46:49], v[166:169], v[206:209], v[46:49]
	v_mfma_f32_16x16x32_bf16 v[14:17], v[174:177], v[206:209], v[14:17]
	v_mfma_f32_16x16x32_bf16 v[66:69], v[178:181], v[194:197], v[54:57]
	v_mfma_f32_16x16x32_bf16 v[38:41], v[170:173], v[202:205], v[38:41]
	v_mfma_f32_16x16x32_bf16 v[2:5], v[178:181], v[202:205], v[2:5]
	v_mfma_f32_16x16x32_bf16 v[46:49], v[170:173], v[210:213], v[46:49]
	v_mfma_f32_16x16x32_bf16 v[14:17], v[178:181], v[210:213], v[14:17]
	s_setprio 0
	s_barrier
	s_add_i32 s38, s38, 2
	s_add_u32 vcc_lo, vcc_lo, 0x100
	s_addc_u32 vcc_hi, vcc_hi, 0
	s_cmp_gt_u32 s38, 13
	s_mov_b64 s[60:61], s[0:1]
	s_cbranch_scc0 .LBB0_1180
	v_readfirstlane_b32 s98, v218
	s_nop 1
	s_lshr_b32 s98, s98, 6
	s_cmp_gt_u32 s98, 3
	s_cbranch_scc1 .Lr_stage_done
	s_mul_i32 s99, s37, 0xfe
	s_add_i32 s99, s99, -2
	s_ashr_i32 s99, s99, 12
	s_mul_i32 s99, s99, 0x5800
	s_add_i32 s99, s99, 0x2c000
	s_add_u32 s100, s68, s99
	s_addc_u32 s101, s69, 0
	s_cmp_eq_u32 s98, 0
	s_cselect_b32 s100, s4, s100
	s_cselect_b32 s101, s5, s101
	s_cmp_eq_u32 s98, 1
	s_cselect_b32 s100, s96, s100
	s_cselect_b32 s101, s97, s101
	s_cmp_eq_u32 s98, 2
	s_cselect_b32 s100, s78, s100
	s_cselect_b32 s101, s79, s101
	s_lshl_b32 s99, s72, 10
	s_add_u32 s100, s100, s99
	s_addc_u32 s101, s101, 0
	s_lshl_b32 s98, s98, 10
	s_add_i32 m0, s98, 0x24000
	v_and_b32_e32 v248, 63, v218
	v_lshlrev_b32_e32 v248, 4, v248
	s_nop 0
	global_load_lds_dwordx4 v248, s[100:101]
.Lr_stage_done:
	s_and_b64 vcc, exec, s[42:43]
	s_cbranch_vccz .LBB0_1183
	s_barrier

.LBB0_1191:
	s_or_b64 exec, exec, s[0:1]
	s_waitcnt vmcnt(0) lgkmcnt(0)
	s_barrier
	s_xor_b64 s[0:1], s[60:61], -1
	v_pk_mul_f32 v[132:133], v[66:67], v[130:131] op_sel:[0,1]
	s_lshl_b32 s37, s72, 8
	v_cndmask_b32_e64 v66, 0, 1, s[10:11]
	v_pk_mul_f32 v[210:211], v[126:127], v[134:135] op_sel_hi:[1,0]
	v_pk_mul_f32 v[212:213], v[128:129], v[134:135] op_sel_hi:[1,0]
	v_pk_mul_f32 v[178:179], v[122:123], v[134:135] op_sel_hi:[1,0]
	v_pk_mul_f32 v[182:183], v[124:125], v[134:135] op_sel_hi:[1,0]
	v_pk_mul_f32 v[214:215], v[110:111], v[134:135] op_sel_hi:[1,0]
	v_pk_mul_f32 v[216:217], v[112:113], v[134:135] op_sel_hi:[1,0]
	v_pk_mul_f32 v[176:177], v[106:107], v[134:135] op_sel_hi:[1,0]
	v_pk_mul_f32 v[180:181], v[108:109], v[134:135] op_sel_hi:[1,0]
	v_pk_mul_f32 v[202:203], v[118:119], v[134:135] op_sel:[0,1]
	v_pk_mul_f32 v[204:205], v[120:121], v[134:135] op_sel:[0,1]
	v_pk_mul_f32 v[172:173], v[114:115], v[134:135] op_sel:[0,1]
	v_pk_mul_f32 v[174:175], v[116:117], v[134:135] op_sel:[0,1]
	v_pk_mul_f32 v[206:207], v[102:103], v[134:135] op_sel:[0,1]
	v_pk_mul_f32 v[208:209], v[104:105], v[134:135] op_sel:[0,1]
	v_pk_mul_f32 v[168:169], v[98:99], v[134:135] op_sel:[0,1]
	v_pk_mul_f32 v[170:171], v[100:101], v[134:135] op_sel:[0,1]
	v_pk_mul_f32 v[194:195], v[94:95], v[130:131] op_sel_hi:[1,0]
	v_pk_mul_f32 v[196:197], v[96:97], v[130:131] op_sel_hi:[1,0]
	v_pk_mul_f32 v[162:163], v[90:91], v[130:131] op_sel_hi:[1,0]
	v_pk_mul_f32 v[166:167], v[92:93], v[130:131] op_sel_hi:[1,0]
	v_pk_mul_f32 v[198:199], v[78:79], v[130:131] op_sel_hi:[1,0]
	v_pk_mul_f32 v[200:201], v[80:81], v[130:131] op_sel_hi:[1,0]
	v_pk_mul_f32 v[160:161], v[74:75], v[130:131] op_sel_hi:[1,0]
	v_pk_mul_f32 v[164:165], v[76:77], v[130:131] op_sel_hi:[1,0]
	v_pk_mul_f32 v[186:187], v[86:87], v[130:131] op_sel:[0,1]
	v_pk_mul_f32 v[188:189], v[88:89], v[130:131] op_sel:[0,1]
	v_pk_mul_f32 v[136:137], v[82:83], v[130:131] op_sel:[0,1]
	v_pk_mul_f32 v[158:159], v[84:85], v[130:131] op_sel:[0,1]
	v_pk_mul_f32 v[190:191], v[70:71], v[130:131] op_sel:[0,1]
	v_pk_mul_f32 v[192:193], v[72:73], v[130:131] op_sel:[0,1]
	v_pk_mul_f32 v[134:135], v[68:69], v[130:131] op_sel:[0,1]
	s_mov_b64 s[62:63], -1
	s_and_b64 vcc, exec, s[0:1]
	v_or_b32_e32 v184, s37, v148
	v_cmp_ne_u32_e64 s[60:61], 1, v66
	s_cbranch_vccnz .LBB0_1194
	s_and_b64 vcc, exec, s[62:63]
	s_cbranch_vccnz .LBB0_1227

.LBB0_1227:
	v_and_b32_e32 v248, 0xff, v184
	v_lshlrev_b32_e32 v248, 2, v248
	v_add_u32_e32 v248, 0x24000, v248
	s_ashr_i32 s0, s17, 12
	s_mulk_i32 s0, 0x5800
	s_ashr_i32 s1, s0, 31
	s_add_u32 s0, s68, s0
	s_addc_u32 s1, s69, s1
	v_ashrrev_i32_e32 v185, 31, v184
	s_add_u32 s0, s0, 0x2c000
	v_lshlrev_b64 v[66:67], 2, v[184:185]
	s_addc_u32 s1, s1, 0
	v_lshl_add_u64 v[68:69], s[4:5], 0, v[66:67]
	v_lshl_add_u64 v[70:71], s[96:97], 0, v[66:67]
	ds_read_b128 v[72:75], v248
	ds_read_b128 v[76:79], v248 offset:1024
	v_lshl_add_u64 v[68:69], s[78:79], 0, v[66:67]
	v_lshl_add_u64 v[66:67], s[0:1], 0, v[66:67]
	ds_read_b128 v[80:83], v248 offset:2048
	ds_read_b128 v[88:91], v248 offset:3072
	v_or_b32_e32 v66, 0x80, v184
	v_ashrrev_i32_e32 v67, 31, v66
	v_lshlrev_b64 v[66:67], 2, v[66:67]
	v_lshl_add_u64 v[68:69], s[4:5], 0, v[66:67]
	v_lshl_add_u64 v[70:71], s[96:97], 0, v[66:67]
	ds_read_b128 v[84:87], v248 offset:512
	ds_read_b128 v[92:95], v248 offset:1536
	v_lshl_add_u64 v[68:69], s[78:79], 0, v[66:67]
	v_lshl_add_u64 v[66:67], s[0:1], 0, v[66:67]
	ds_read_b128 v[96:99], v248 offset:2560
	ds_read_b128 v[100:103], v248 offset:3584
	v_mov_b32_e32 v108, 0
	s_and_b64 vcc, exec, s[60:61]
	v_mov_b32_e32 v112, 0
	v_mov_b32_e32 v113, 0
	v_mov_b32_e32 v114, 0
	v_mov_b32_e32 v115, 0
	v_mov_b32_e32 v66, 0
	v_mov_b32_e32 v67, 0
	v_mov_b32_e32 v68, 0
	v_mov_b32_e32 v69, 0
	s_cbranch_vccnz .LBB0_1229
	ds_read_b128 v[66:69], v221
	ds_read_b128 v[112:115], v222

.LBB0_1235:
	v_pk_fma_f32 v[54:55], v[196:197], v[82:83], v[90:91]
	v_pk_fma_f32 v[108:109], v[194:195], v[80:81], v[88:89]
	v_pk_fma_f32 v[54:55], v[78:79], v[52:53], v[54:55]
	s_waitcnt lgkmcnt(1)
	v_mov_b32_dpp v60, v48 row_shr:1 row_mask:0xf bank_mask:0xf
	v_mov_b32_dpp v61, v49 row_shr:1 row_mask:0xf bank_mask:0xf
	v_pk_fma_f32 v[108:109], v[76:77], v[50:51], v[108:109]
	v_pk_fma_f32 v[54:55], v[74:75], v[106:107], v[54:55]
	v_pk_fma_f32 v[106:107], v[200:201], v[98:99], v[102:103]
	s_waitcnt lgkmcnt(0)
	v_mov_b32_dpp v64, v40 row_shr:1 row_mask:0xf bank_mask:0xf
	v_mov_b32_dpp v65, v41 row_shr:1 row_mask:0xf bank_mask:0xf
	v_pk_fma_f32 v[104:105], v[72:73], v[104:105], v[108:109]
	v_pk_fma_f32 v[106:107], v[94:95], v[60:61], v[106:107]
	v_mov_b32_dpp v58, v46 row_shr:1 row_mask:0xf bank_mask:0xf
	v_pk_fma_f32 v[64:65], v[86:87], v[64:65], v[106:107]
	v_mul_f32_e32 v106, 0xbfb8aa3b, v104
	v_exp_f32_e32 v106, v106
	v_mov_b32_dpp v59, v47 row_shr:1 row_mask:0xf bank_mask:0xf
	v_pk_fma_f32 v[108:109], v[198:199], v[96:97], v[100:101]
	v_mov_b32_dpp v62, v38 row_shr:1 row_mask:0xf bank_mask:0xf
	v_add_f32_e32 v106, 1.0, v106
	v_rcp_f32_e32 v106, v106
	v_mov_b32_dpp v63, v39 row_shr:1 row_mask:0xf bank_mask:0xf
	v_pk_fma_f32 v[108:109], v[92:93], v[58:59], v[108:109]
	v_pk_fma_f32 v[42:43], v[42:43], v[80:81], v[88:89]
	v_pk_fma_f32 v[62:63], v[84:85], v[62:63], v[108:109]
	v_mul_f32_e32 v104, v104, v106
	v_mul_f32_e32 v62, v104, v62
	v_mul_f32_e32 v104, 0xbfb8aa3b, v105
	v_exp_f32_e32 v104, v104
	v_pk_fma_f32 v[44:45], v[44:45], v[82:83], v[90:91]
	s_and_b64 vcc, exec, s[60:61]
	v_add_f32_e32 v104, 1.0, v104
	v_rcp_f32_e32 v104, v104
	s_nop 0
	v_mul_f32_e32 v104, v105, v104
	v_mul_f32_e32 v63, v104, v63
	v_mul_f32_e32 v104, 0xbfb8aa3b, v54
	v_exp_f32_e32 v104, v104
	v_mov_b32_e32 v105, 0
	v_add_f32_e32 v104, 1.0, v104
	v_rcp_f32_e32 v104, v104
	s_nop 0
	v_mul_f32_e32 v54, v54, v104
	v_mul_f32_e32 v64, v54, v64
	v_mul_f32_e32 v54, 0xbfb8aa3b, v55
	v_exp_f32_e32 v54, v54
	v_mov_b32_e32 v104, 0
	v_add_f32_e32 v54, 1.0, v54
	v_rcp_f32_e32 v54, v54
	s_nop 0
	v_mul_f32_e32 v54, v55, v54
	v_mul_f32_e32 v55, v54, v65
	v_cvt_pk_bf16_f32 v54, v62, v63
	v_pk_fma_f32 v[62:63], v[188:189], v[82:83], v[90:91]
	v_cvt_pk_bf16_f32 v55, v64, v55
	v_pk_fma_f32 v[64:65], v[186:187], v[80:81], v[88:89]
	v_pk_fma_f32 v[62:63], v[196:197], v[78:79], v[62:63]
	v_pk_fma_f32 v[64:65], v[194:195], v[76:77], v[64:65]
	v_pk_fma_f32 v[52:53], v[74:75], v[52:53], v[62:63]
	v_pk_fma_f32 v[62:63], v[192:193], v[98:99], v[102:103]
	v_pk_fma_f32 v[50:51], v[72:73], v[50:51], v[64:65]
	v_pk_fma_f32 v[62:63], v[200:201], v[94:95], v[62:63]
	v_pk_fma_f32 v[64:65], v[190:191], v[96:97], v[100:101]
	v_pk_fma_f32 v[60:61], v[86:87], v[60:61], v[62:63]
	v_mul_f32_e32 v62, 0xbfb8aa3b, v50
	v_exp_f32_e32 v62, v62
	v_pk_fma_f32 v[64:65], v[198:199], v[92:93], v[64:65]
	v_add_f32_e32 v62, 1.0, v62
	v_rcp_f32_e32 v62, v62
	v_pk_fma_f32 v[58:59], v[84:85], v[58:59], v[64:65]
	v_mul_f32_e32 v50, v50, v62
	v_mul_f32_e32 v50, v50, v58
	v_mul_f32_e32 v58, 0xbfb8aa3b, v51
	v_exp_f32_e32 v58, v58
	v_pk_fma_f32 v[62:63], v[38:39], v[96:97], v[100:101]
	v_add_f32_e32 v58, 1.0, v58
	v_rcp_f32_e32 v58, v58
	v_pk_fma_f32 v[62:63], v[190:191], v[92:93], v[62:63]
	v_mul_f32_e32 v51, v51, v58
	v_mul_f32_e32 v58, 0xbfb8aa3b, v52
	v_exp_f32_e32 v58, v58
	v_mul_f32_e32 v51, v51, v59
	v_pk_fma_f32 v[62:63], v[198:199], v[84:85], v[62:63]
	v_add_f32_e32 v58, 1.0, v58
	v_rcp_f32_e32 v58, v58
	s_nop 0
	v_mul_f32_e32 v52, v52, v58
	v_mul_f32_e32 v58, v52, v60
	v_mul_f32_e32 v52, 0xbfb8aa3b, v53
	v_exp_f32_e32 v52, v52
	s_nop 0
	v_add_f32_e32 v52, 1.0, v52
	v_rcp_f32_e32 v52, v52
	s_nop 0
	v_mul_f32_e32 v52, v53, v52
	v_mul_f32_e32 v53, v52, v61
	v_cvt_pk_bf16_f32 v53, v58, v53
	v_pk_fma_f32 v[58:59], v[34:35], v[80:81], v[88:89]
	v_pk_fma_f32 v[34:35], v[34:35], v[76:77], v[42:43]
	v_pk_fma_f32 v[42:43], v[48:49], v[98:99], v[102:103]
	v_pk_fma_f32 v[34:35], v[186:187], v[72:73], v[34:35]
	v_pk_fma_f32 v[60:61], v[40:41], v[98:99], v[102:103]
	v_pk_fma_f32 v[40:41], v[40:41], v[94:95], v[42:43]
	v_mul_f32_e32 v42, 0xbfb8aa3b, v34
	v_exp_f32_e32 v42, v42
	v_pk_fma_f32 v[58:59], v[186:187], v[76:77], v[58:59]
	v_cvt_pk_bf16_f32 v52, v50, v51
	v_pk_fma_f32 v[50:51], v[36:37], v[82:83], v[90:91]
	v_add_f32_e32 v42, 1.0, v42
	v_pk_fma_f32 v[58:59], v[194:195], v[72:73], v[58:59]
	v_rcp_f32_e32 v42, v42
	v_mul_f32_e32 v64, 0xbfb8aa3b, v58
	v_exp_f32_e32 v64, v64
	v_pk_fma_f32 v[36:37], v[36:37], v[78:79], v[44:45]
	v_pk_fma_f32 v[44:45], v[46:47], v[96:97], v[100:101]
	v_mul_f32_e32 v34, v34, v42
	v_pk_fma_f32 v[38:39], v[38:39], v[92:93], v[44:45]
	v_add_f32_e32 v64, 1.0, v64
	v_pk_fma_f32 v[38:39], v[190:191], v[84:85], v[38:39]
	v_rcp_f32_e32 v64, v64
	v_mul_f32_e32 v34, v38, v34
	v_mul_f32_e32 v38, 0xbfb8aa3b, v35
	v_exp_f32_e32 v38, v38
	v_mul_f32_e32 v58, v58, v64
	v_mul_f32_e32 v58, v62, v58
	v_mul_f32_e32 v62, 0xbfb8aa3b, v59
	v_add_f32_e32 v38, 1.0, v38
	v_rcp_f32_e32 v38, v38
	v_exp_f32_e32 v62, v62
	v_pk_fma_f32 v[36:37], v[188:189], v[74:75], v[36:37]
	v_pk_fma_f32 v[50:51], v[188:189], v[78:79], v[50:51]
	v_mul_f32_e32 v35, v35, v38
	v_mul_f32_e32 v38, 0xbfb8aa3b, v36
	v_exp_f32_e32 v38, v38
	v_add_f32_e32 v62, 1.0, v62
	v_rcp_f32_e32 v62, v62
	v_pk_fma_f32 v[50:51], v[196:197], v[74:75], v[50:51]
	v_add_f32_e32 v38, 1.0, v38
	v_rcp_f32_e32 v38, v38
	v_mul_f32_e32 v59, v59, v62
	v_mul_f32_e32 v62, 0xbfb8aa3b, v50
	v_exp_f32_e32 v62, v62
	v_mul_f32_e32 v36, v36, v38
	v_mul_f32_e32 v38, 0xbfb8aa3b, v37
	v_exp_f32_e32 v38, v38
	v_add_f32_e32 v62, 1.0, v62
	v_rcp_f32_e32 v62, v62
	v_pk_fma_f32 v[60:61], v[192:193], v[94:95], v[60:61]
	v_add_f32_e32 v38, 1.0, v38
	v_rcp_f32_e32 v38, v38
	v_pk_fma_f32 v[60:61], v[200:201], v[86:87], v[60:61]
	v_mul_f32_e32 v50, v50, v62
	v_mul_f32_e32 v60, v60, v50
	v_mul_f32_e32 v50, 0xbfb8aa3b, v51
	v_exp_f32_e32 v50, v50
	v_pk_fma_f32 v[40:41], v[192:193], v[86:87], v[40:41]
	v_mul_f32_e32 v35, v39, v35
	v_mul_f32_e32 v36, v40, v36
	v_mul_f32_e32 v37, v37, v38
	v_mul_f32_e32 v37, v41, v37
	v_cvt_pk_bf16_f32 v34, v34, v35
	v_cvt_pk_bf16_f32 v35, v36, v37
	v_or_b32_e32 v36, 4, v184
	v_ashrrev_i32_e32 v37, 31, v36
	v_add_f32_e32 v50, 1.0, v50
	v_lshlrev_b64 v[40:41], 2, v[36:37]
	v_rcp_f32_e32 v50, v50
	v_lshl_add_u64 v[42:43], s[96:97], 0, v[40:41]
	v_lshl_add_u64 v[36:37], s[4:5], 0, v[40:41]
	ds_read_b128 v[44:47], v248 offset:1040
	v_lshl_add_u64 v[42:43], s[78:79], 0, v[40:41]
	v_lshl_add_u64 v[40:41], s[0:1], 0, v[40:41]
	ds_read_b128 v[36:39], v248 offset:16
	v_mul_f32_e32 v59, v63, v59
	ds_read_b128 v[78:81], v248 offset:3088
	v_or_b32_e32 v40, 0x84, v184
	v_ashrrev_i32_e32 v41, 31, v40
	v_mul_f32_e32 v50, v51, v50
	v_lshlrev_b64 v[48:49], 2, v[40:41]
	v_mul_f32_e32 v51, v61, v50
	v_cvt_pk_bf16_f32 v50, v58, v59
	v_lshl_add_u64 v[58:59], s[96:97], 0, v[48:49]
	v_cvt_pk_bf16_f32 v51, v60, v51
	ds_read_b128 v[60:63], v248 offset:2064
	ds_read_b128 v[74:77], v248 offset:1552
	v_lshl_add_u64 v[40:41], s[4:5], 0, v[48:49]
	v_lshl_add_u64 v[58:59], s[78:79], 0, v[48:49]
	v_lshl_add_u64 v[48:49], s[0:1], 0, v[48:49]
	ds_read_b128 v[40:43], v248 offset:528
	v_mov_b32_e32 v98, 0
	ds_read_b128 v[82:85], v248 offset:2576
	ds_read_b128 v[86:89], v248 offset:3600
	v_mov_b32_e32 v102, 0
	v_mov_b32_e32 v103, 0
	v_mov_b32_e32 v90, 0
	v_mov_b32_e32 v91, 0
	v_mov_b32_e32 v92, 0
	v_mov_b32_e32 v93, 0
	s_cbranch_vccnz .LBB0_1237
	ds_read_b128 v[90:93], v221 offset:16
	ds_read_b128 v[102:105], v222 offset:16

	.amdhsa_kernel _Z14fwd_megakernel4Args
		.amdhsa_group_segment_fixed_size 4096
		.amdhsa_private_segment_fixed_size 0
		.amdhsa_kernarg_size 472
		.amdhsa_user_sgpr_count 2
		.amdhsa_user_sgpr_dispatch_ptr 0
		.amdhsa_user_sgpr_queue_ptr 0
		.amdhsa_user_sgpr_kernarg_segment_ptr 1
		.amdhsa_user_sgpr_dispatch_id 0
		.amdhsa_user_sgpr_kernarg_preload_length 0
		.amdhsa_user_sgpr_kernarg_preload_offset 0
		.amdhsa_user_sgpr_private_segment_size 0
		.amdhsa_uses_dynamic_stack 0
		.amdhsa_enable_private_segment 0
		.amdhsa_system_sgpr_workgroup_id_x 1
		.amdhsa_system_sgpr_workgroup_id_y 0
		.amdhsa_system_sgpr_workgroup_id_z 0
		.amdhsa_system_sgpr_workgroup_info 0
		.amdhsa_system_vgpr_workitem_id 2
		.amdhsa_next_free_vgpr 256
		.amdhsa_next_free_sgpr 102
		.amdhsa_accum_offset 256
		.amdhsa_reserve_vcc 1
		.amdhsa_float_round_mode_32 0
		.amdhsa_float_round_mode_16_64 0
		.amdhsa_float_denorm_mode_32 3
		.amdhsa_float_denorm_mode_16_64 3
		.amdhsa_dx10_clamp 1
		.amdhsa_ieee_mode 1
		.amdhsa_fp16_overflow 0
		.amdhsa_tg_split 0
		.amdhsa_exception_fp_ieee_invalid_op 0
		.amdhsa_exception_fp_denorm_src 0
		.amdhsa_exception_fp_ieee_div_zero 0
		.amdhsa_exception_fp_ieee_overflow 0
		.amdhsa_exception_fp_ieee_underflow 0
		.amdhsa_exception_fp_ieee_inexact 0
		.amdhsa_exception_int_div_zero 0
	.end_amdhsa_kernel

amdhsa.kernels:
  - .agpr_count:     0
    .args:
      - .offset:         0
        .size:           216
        .value_kind:     by_value
      - .offset:         216
        .size:           4
        .value_kind:     hidden_block_count_x
      - .offset:         220
        .size:           4
        .value_kind:     hidden_block_count_y
      - .offset:         224
        .size:           4
        .value_kind:     hidden_block_count_z
      - .offset:         228
        .size:           2
        .value_kind:     hidden_group_size_x
      - .offset:         230
        .size:           2
        .value_kind:     hidden_group_size_y
      - .offset:         232
        .size:           2
        .value_kind:     hidden_group_size_z
      - .offset:         234
        .size:           2
        .value_kind:     hidden_remainder_x
      - .offset:         236
        .size:           2
        .value_kind:     hidden_remainder_y
      - .offset:         238
        .size:           2
        .value_kind:     hidden_remainder_z
      - .offset:         256
        .size:           8
        .value_kind:     hidden_global_offset_x
      - .offset:         264
        .size:           8
        .value_kind:     hidden_global_offset_y
      - .offset:         272
        .size:           8
        .value_kind:     hidden_global_offset_z
      - .offset:         280
        .size:           2
        .value_kind:     hidden_grid_dims
      - .offset:         304
        .size:           8
        .value_kind:     hidden_multigrid_sync_arg
      - .offset:         336
        .size:           4
        .value_kind:     hidden_dynamic_lds_size
    .group_segment_fixed_size: 4096
    .kernarg_segment_align: 8
    .kernarg_segment_size: 472
    .language:       OpenCL C
    .language_version:
      - 2
      - 0
    .max_flat_workgroup_size: 512
    .name:           _Z14fwd_megakernel4Args
    .private_segment_fixed_size: 0
    .sgpr_count:     108
    .sgpr_spill_count: 95
    .symbol:         _Z14fwd_megakernel4Args.kd
    .uniform_work_group_size: 1
    .uses_dynamic_stack: false
    .vgpr_count:     256
    .vgpr_spill_count: 0
    .wavefront_size: 64
